# diff-attention unit epilogue: the 16 output-gain vector loads issued together instead of one load plus a full wait per 8 columns
# speedup vs baseline: 1.0077x; 1.0011x over previous
; #define ATT_LAS __attribute__((address_space(3)))
; __device__ __forceinline__ void diff_unit(ATT_LAS unsigned char* lds, int b, int h, int qb, const bf16_t* __restrict__ DQ, const bf16_t* __restrict__ DK, const bf16_t* __restrict__ VT,
;                                           float lam, const float* __restrict__ gout, bf16_t* __restrict__ MIXED) {
;     ...
;     __syncthreads();
;     lsum += __shfl_xor(lsum, 32);
;     const float inv = 1.0f / lsum;
;     ATT_LAS float* X = (ATT_LAS float*)lds;
;     if (comp == 1) { const float f = inv * lam;
; #pragma unroll
;         for (int e = 0; e < 4; ++e)
; #pragma unroll
;             for (int i = 0; i < 16; ++i) X[((wq * 4 + e) * 16 + i) * 64 + lane] = O[e][i] * f; }
;     __syncthreads();
;     if (comp == 0) {
;         float ss = 0.f;
; #pragma unroll
;         for (int e = 0; e < 4; ++e)
; #pragma unroll
;             for (int i = 0; i < 16; ++i) { const float o = O[e][i] * inv - X[((wq * 4 + e) * 16 + i) * 64 + lane]; O[e][i] = o; ss += o * o; }
;         ss += __shfl_xor(ss, 32);
;         const float rstd = rsqrtf(ss * (1.0f / 128.0f) + EPS) * 0.8f;
;         ATT_LAS unsigned char* stg = lds + 65536 + wq * OSTG_BYTES;
; #pragma unroll
;         for (int e = 0; e < 4; ++e)
; #pragma unroll
;             for (int g4 = 0; g4 < 4; ++g4) { const int e0 = 32 * e + 8 * g4 + 4 * hh; const f32x4 g = *(const f32x4*)(gout + e0);
.LBB0_558:
	s_cmpk_gt_u32 s40, 0xff
	s_waitcnt lgkmcnt(0)
	s_barrier
	s_cbranch_scc1 .LBB0_527
	s_lshl_b32 s4, s40, 8
	s_and_b32 s22, s4, 0xc000
	v_add_u32_e32 v1, s22, v197
	ds_read2st64_b32 v[4:5], v1 offset1:1
	ds_read2st64_b32 v[6:7], v1 offset0:2 offset1:3
	ds_read2st64_b32 v[8:9], v1 offset0:4 offset1:5
	ds_read2st64_b32 v[10:11], v1 offset0:6 offset1:7
	s_or_b32 s4, s4, 0x3f00
	s_waitcnt lgkmcnt(3)
	v_fma_f32 v64, v64, v2, -v4
	v_fma_f32 v65, v65, v2, -v5
	s_waitcnt lgkmcnt(2)
	v_fma_f32 v66, v66, v2, -v6
	v_fma_f32 v67, v67, v2, -v7
	s_waitcnt lgkmcnt(1)
	v_fma_f32 v68, v68, v2, -v8
	v_fma_f32 v69, v69, v2, -v9
	s_waitcnt lgkmcnt(0)
	v_fma_f32 v70, v70, v2, -v10
	v_fma_f32 v71, v71, v2, -v11
	ds_read2st64_b32 v[4:5], v1 offset0:8 offset1:9
	ds_read2st64_b32 v[6:7], v1 offset0:10 offset1:11
	ds_read2st64_b32 v[8:9], v1 offset0:12 offset1:13
	ds_read2st64_b32 v[10:11], v1 offset0:14 offset1:15
	v_mul_f32_e32 v3, v65, v65
	v_fmac_f32_e32 v3, v64, v64
	s_waitcnt lgkmcnt(2)
	v_fma_f32 v74, v74, v2, -v6
	v_fma_f32 v72, v72, v2, -v4
	v_fma_f32 v73, v73, v2, -v5
	v_fma_f32 v75, v75, v2, -v7
	s_waitcnt lgkmcnt(1)
	v_fma_f32 v76, v76, v2, -v8
	v_fma_f32 v77, v77, v2, -v9
	s_waitcnt lgkmcnt(0)
	v_fma_f32 v78, v78, v2, -v10
	v_fma_f32 v79, v79, v2, -v11
	ds_read2st64_b32 v[4:5], v1 offset0:16 offset1:17
	ds_read2st64_b32 v[6:7], v1 offset0:18 offset1:19
	ds_read2st64_b32 v[8:9], v1 offset0:20 offset1:21
	ds_read2st64_b32 v[10:11], v1 offset0:22 offset1:23
	v_fmac_f32_e32 v3, v66, v66
	v_fmac_f32_e32 v3, v67, v67
	s_waitcnt lgkmcnt(2)
	v_fma_f32 v50, v50, v2, -v6
	v_fma_f32 v48, v48, v2, -v4
	v_fma_f32 v49, v49, v2, -v5
	v_fma_f32 v51, v51, v2, -v7
	s_waitcnt lgkmcnt(1)
	v_fma_f32 v52, v52, v2, -v8
	v_fma_f32 v53, v53, v2, -v9
	s_waitcnt lgkmcnt(0)
	v_fma_f32 v54, v54, v2, -v10
	v_fma_f32 v55, v55, v2, -v11
	ds_read2st64_b32 v[4:5], v1 offset0:24 offset1:25
	ds_read2st64_b32 v[6:7], v1 offset0:26 offset1:27
	ds_read2st64_b32 v[8:9], v1 offset0:28 offset1:29
	ds_read2st64_b32 v[10:11], v1 offset0:30 offset1:31
	v_fmac_f32_e32 v3, v68, v68
	v_fmac_f32_e32 v3, v69, v69
	v_fmac_f32_e32 v3, v70, v70
	v_fmac_f32_e32 v3, v71, v71
	v_fmac_f32_e32 v3, v72, v72
	s_waitcnt lgkmcnt(3)
	v_fma_f32 v56, v56, v2, -v4
	v_fma_f32 v57, v57, v2, -v5
	s_waitcnt lgkmcnt(2)
	v_fma_f32 v58, v58, v2, -v6
	v_fma_f32 v59, v59, v2, -v7
	s_waitcnt lgkmcnt(1)
	v_fma_f32 v60, v60, v2, -v8
	v_fma_f32 v61, v61, v2, -v9
	s_waitcnt lgkmcnt(0)
	v_fma_f32 v62, v62, v2, -v10
	v_fma_f32 v63, v63, v2, -v11
	ds_read2st64_b32 v[4:5], v1 offset0:32 offset1:33
	ds_read2st64_b32 v[6:7], v1 offset0:34 offset1:35
	ds_read2st64_b32 v[8:9], v1 offset0:36 offset1:37
	ds_read2st64_b32 v[10:11], v1 offset0:38 offset1:39
	global_load_dwordx4 v[112:115], v[158:159], off
	global_load_dwordx4 v[116:119], v[158:159], off offset:32
	global_load_dwordx4 v[120:123], v[158:159], off offset:64
	global_load_dwordx4 v[124:127], v[158:159], off offset:96
	global_load_dwordx4 v[128:131], v[158:159], off offset:128
	global_load_dwordx4 v[132:135], v[158:159], off offset:160
	global_load_dwordx4 v[136:139], v[158:159], off offset:192
	global_load_dwordx4 v[140:143], v[158:159], off offset:224
	global_load_dwordx4 v[218:221], v[158:159], off offset:256
	global_load_dwordx4 v[222:225], v[158:159], off offset:288
	global_load_dwordx4 v[226:229], v[158:159], off offset:320
	global_load_dwordx4 v[230:233], v[158:159], off offset:352
	global_load_dwordx4 v[234:237], v[158:159], off offset:384
	global_load_dwordx4 v[240:243], v[158:159], off offset:416
	global_load_dwordx4 v[244:247], v[158:159], off offset:448
	global_load_dwordx4 v[248:251], v[158:159], off offset:480
	v_fmac_f32_e32 v3, v73, v73
	v_fmac_f32_e32 v3, v74, v74
	v_fmac_f32_e32 v3, v75, v75
	v_fmac_f32_e32 v3, v76, v76
	v_fmac_f32_e32 v3, v77, v77
	v_fmac_f32_e32 v3, v78, v78
	v_fmac_f32_e32 v3, v79, v79
	v_fmac_f32_e32 v3, v48, v48
	v_fmac_f32_e32 v3, v49, v49
	v_fmac_f32_e32 v3, v50, v50
	v_fmac_f32_e32 v3, v51, v51
	v_fmac_f32_e32 v3, v52, v52
	v_fmac_f32_e32 v3, v53, v53
	v_fmac_f32_e32 v3, v54, v54
	v_fmac_f32_e32 v3, v55, v55
	v_fmac_f32_e32 v3, v56, v56
	v_fmac_f32_e32 v3, v57, v57
	v_fmac_f32_e32 v3, v58, v58
	v_fmac_f32_e32 v3, v59, v59
	v_fmac_f32_e32 v3, v60, v60
	v_fmac_f32_e32 v3, v61, v61
	v_fmac_f32_e32 v3, v62, v62
	v_fmac_f32_e32 v3, v63, v63
	s_waitcnt lgkmcnt(3)
	v_fma_f32 v32, v32, v2, -v4
	v_fmac_f32_e32 v3, v32, v32
	v_fma_f32 v33, v33, v2, -v5
	v_fmac_f32_e32 v3, v33, v33
	s_waitcnt lgkmcnt(2)
	v_fma_f32 v34, v34, v2, -v6
	v_fmac_f32_e32 v3, v34, v34
	v_fma_f32 v35, v35, v2, -v7
	ds_read2st64_b32 v[4:5], v1 offset0:40 offset1:41
	v_fmac_f32_e32 v3, v35, v35
	s_waitcnt lgkmcnt(2)
	v_fma_f32 v36, v36, v2, -v8
	v_fmac_f32_e32 v3, v36, v36
	v_fma_f32 v37, v37, v2, -v9
	v_fmac_f32_e32 v3, v37, v37
	s_waitcnt lgkmcnt(1)
	v_fma_f32 v38, v38, v2, -v10
	v_fmac_f32_e32 v3, v38, v38
	v_fma_f32 v39, v39, v2, -v11
	ds_read2st64_b32 v[6:7], v1 offset0:42 offset1:43
	ds_read2st64_b32 v[8:9], v1 offset0:44 offset1:45
	ds_read2st64_b32 v[10:11], v1 offset0:46 offset1:47
	v_fmac_f32_e32 v3, v39, v39
	s_waitcnt lgkmcnt(3)
	v_fma_f32 v40, v40, v2, -v4
	v_fmac_f32_e32 v3, v40, v40
	v_fma_f32 v41, v41, v2, -v5
	v_fmac_f32_e32 v3, v41, v41
	s_waitcnt lgkmcnt(2)
	v_fma_f32 v42, v42, v2, -v6
	v_fmac_f32_e32 v3, v42, v42
	v_fma_f32 v43, v43, v2, -v7
	ds_read2st64_b32 v[4:5], v1 offset0:48 offset1:49
	v_fmac_f32_e32 v3, v43, v43
	s_waitcnt lgkmcnt(2)
	v_fma_f32 v44, v44, v2, -v8
	v_fmac_f32_e32 v3, v44, v44
	v_fma_f32 v45, v45, v2, -v9
	v_fmac_f32_e32 v3, v45, v45
	s_waitcnt lgkmcnt(1)
; __device__ __forceinline__ unsigned cvt_pk_bf16(float lo, float hi) { unsigned r; asm volatile("v_cvt_pk_bf16_f32 %0, %1, %2" : "=v"(r) : "v"(lo), "v"(hi)); return r; }
; #define ATT_LAS __attribute__((address_space(3)))
; __device__ __forceinline__ void diff_unit(ATT_LAS unsigned char* lds, int b, int h, int qb, const bf16_t* __restrict__ DQ, const bf16_t* __restrict__ DK, const bf16_t* __restrict__ VT,
;                                           float lam, const float* __restrict__ gout, bf16_t* __restrict__ MIXED) {
;     ...
;             for (int i = 0; i < 16; ++i) { const float o = O[e][i] * inv - X[((wq * 4 + e) * 16 + i) * 64 + lane]; O[e][i] = o; ss += o * o; }
;         ss += __shfl_xor(ss, 32);
;         const float rstd = rsqrtf(ss * (1.0f / 128.0f) + EPS) * 0.8f;
;         ATT_LAS unsigned char* stg = lds + 65536 + wq * OSTG_BYTES;
; #pragma unroll
;         for (int e = 0; e < 4; ++e)
; #pragma unroll
;             for (int g4 = 0; g4 < 4; ++g4) { const int e0 = 32 * e + 8 * g4 + 4 * hh; const f32x4 g = *(const f32x4*)(gout + e0);
;                 u32x2 w; w.x = cvt_pk_bf16(O[e][4 * g4] * rstd * g[0], O[e][4 * g4 + 1] * rstd * g[1]); w.y = cvt_pk_bf16(O[e][4 * g4 + 2] * rstd * g[2], O[e][4 * g4 + 3] * rstd * g[3]);
;                 *(ATT_LAS u32x2*)(stg + r * OSTG_PITCH + e0 * 2) = w; }
	v_fma_f32 v46, v46, v2, -v10
	v_fmac_f32_e32 v3, v46, v46
	v_fma_f32 v47, v47, v2, -v11
	ds_read2st64_b32 v[6:7], v1 offset0:50 offset1:51
	ds_read2st64_b32 v[8:9], v1 offset0:52 offset1:53
	ds_read2st64_b32 v[10:11], v1 offset0:54 offset1:55
	v_fmac_f32_e32 v3, v47, v47
	s_waitcnt lgkmcnt(3)
	v_fma_f32 v80, v16, v2, -v4
	v_fmac_f32_e32 v3, v80, v80
	v_fma_f32 v81, v17, v2, -v5
	v_fmac_f32_e32 v3, v81, v81
	s_waitcnt lgkmcnt(2)
	v_fma_f32 v82, v18, v2, -v6
	v_fmac_f32_e32 v3, v82, v82
	v_fma_f32 v83, v19, v2, -v7
	v_fmac_f32_e32 v3, v83, v83
	s_waitcnt lgkmcnt(1)
	v_fma_f32 v20, v20, v2, -v8
	v_fmac_f32_e32 v3, v20, v20
	v_fma_f32 v21, v21, v2, -v9
	v_fmac_f32_e32 v3, v21, v21
	ds_read2st64_b32 v[6:7], v1 offset0:56 offset1:57
	s_waitcnt lgkmcnt(1)
	v_pk_fma_f32 v[10:11], v[22:23], v[2:3], v[10:11] op_sel_hi:[1,0,1] neg_lo:[0,0,1] neg_hi:[0,0,1]
	s_mulk_i32 s39, 0x2200
	v_pk_mul_f32 v[4:5], v[10:11], v[10:11]
	s_or_b32 s22, s37, s38
	v_add_f32_e32 v3, v3, v4
	v_add_f32_e32 v3, v3, v5
	ds_read2st64_b32 v[4:5], v1 offset0:58 offset1:59
	ds_read2st64_b32 v[16:17], v1 offset0:60 offset1:61
	ds_read_b32 v18, v1 offset:15872
	s_waitcnt lgkmcnt(3)
	v_pk_fma_f32 v[8:9], v[24:25], v[2:3], v[6:7] op_sel_hi:[1,0,1] neg_lo:[0,0,1] neg_hi:[0,0,1]
	s_ashr_i32 s23, s22, 31
	v_pk_mul_f32 v[6:7], v[8:9], v[8:9]
	s_lshl_b64 s[22:23], s[22:23], 12
	v_add_f32_e32 v1, v3, v6
	v_add_f32_e32 v1, v1, v7
	s_waitcnt lgkmcnt(2)
	v_pk_fma_f32 v[6:7], v[26:27], v[2:3], v[4:5] op_sel_hi:[1,0,1] neg_lo:[0,0,1] neg_hi:[0,0,1]
	v_add_u32_e32 v3, s4, v197
	ds_read_b32 v19, v3
	v_pk_mul_f32 v[4:5], v[6:7], v[6:7]
	s_add_i32 s4, s39, 0
	v_add_f32_e32 v1, v1, v4
	v_add_f32_e32 v1, v1, v5
	s_waitcnt lgkmcnt(2)
	v_pk_fma_f32 v[4:5], v[28:29], v[2:3], v[16:17] op_sel_hi:[1,0,1] neg_lo:[0,0,1] neg_hi:[0,0,1]
	s_waitcnt lgkmcnt(0)
	v_pk_fma_f32 v[2:3], v[30:31], v[2:3], v[18:19] op_sel_hi:[1,0,1] neg_lo:[0,0,1] neg_hi:[0,0,1]
	v_pk_mul_f32 v[16:17], v[4:5], v[4:5]
	s_add_i32 s4, s4, 0x10000
	v_add_f32_e32 v1, v1, v16
	v_add_f32_e32 v1, v1, v17
	v_pk_mul_f32 v[16:17], v[2:3], v[2:3]
	v_add_u32_e32 v18, s4, v198
	v_add_f32_e32 v1, v1, v16
	v_add_f32_e32 v1, v1, v17
	ds_bpermute_b32 v16, v187, v1
	v_add_u32_e32 v19, v18, v156
	s_add_u32 s22, s90, s22
	v_add3_u32 v30, s4, v191, v214
	s_addc_u32 s4, s91, s23
	s_waitcnt lgkmcnt(0)
	v_add_f32_e32 v1, v1, v16
	v_fmamk_f32 v1, v1, 0x3c000000, v216
	v_mul_f32_e32 v16, 0x4b800000, v1
	v_cmp_gt_f32_e32 vcc, s35, v1
	s_lshl_b32 s23, s36, 1
	s_add_u32 s22, s22, s23
	v_cndmask_b32_e32 v1, v1, v16, vcc
	v_rsq_f32_e32 v1, v1
	v_mov_b32_e32 v161, v0
	s_addc_u32 s23, s4, 0
	v_mov_b32_e32 v167, v0
	v_mul_f32_e32 v16, 0x45800000, v1
	v_cndmask_b32_e32 v1, v1, v16, vcc
	v_mul_f32_e32 v1, 0x3f4ccccd, v1
	v_mul_f32_e32 v16, v64, v1
	s_waitcnt vmcnt(0)
	v_mul_f32_e32 v12, v112, v16
	v_mul_f32_e32 v16, v65, v1
	v_mul_f32_e32 v13, v113, v16
	v_cvt_pk_bf16_f32 v16, v12, v13
	v_mul_f32_e32 v12, v66, v1
	v_mul_f32_e32 v13, v67, v1
	v_mul_f32_e32 v12, v114, v12
	v_mul_f32_e32 v13, v115, v13
	v_cvt_pk_bf16_f32 v17, v12, v13
	ds_write_b64 v19, v[16:17]
	v_mul_f32_e32 v16, v68, v1
	v_mul_f32_e32 v22, v72, v1
	v_mul_f32_e32 v23, v73, v1
	v_mul_f32_e32 v24, v74, v1
	v_mul_f32_e32 v25, v75, v1
	v_add_u32_e32 v19, v18, v199
	v_mul_f32_e32 v20, v20, v1
	v_mul_f32_e32 v21, v21, v1
	v_mul_f32_e32 v10, v10, v1
	v_mul_f32_e32 v11, v11, v1
	v_mul_f32_e32 v8, v8, v1
	v_mul_f32_e32 v9, v9, v1
	v_mul_f32_e32 v6, v6, v1
	v_mul_f32_e32 v7, v7, v1
	v_mul_f32_e32 v4, v4, v1
	v_mul_f32_e32 v5, v5, v1
	v_mul_f32_e32 v2, v2, v1
	v_mov_b32_e32 v169, v0
	v_mov_b32_e32 v171, v0
	v_mov_b32_e32 v173, v0
	v_mov_b32_e32 v175, v0
	v_mov_b32_e32 v177, v0
	v_mov_b32_e32 v179, v0
	v_mov_b32_e32 v181, v0
	v_mul_f32_e32 v12, v116, v16
	v_mul_f32_e32 v16, v69, v1
	v_mul_f32_e32 v13, v117, v16
	v_cvt_pk_bf16_f32 v16, v12, v13
	v_mul_f32_e32 v12, v70, v1
	v_mul_f32_e32 v13, v71, v1
	v_mul_f32_e32 v12, v118, v12
	v_mul_f32_e32 v13, v119, v13
	v_cvt_pk_bf16_f32 v17, v12, v13
	ds_write_b64 v19, v[16:17]
	v_add_u32_e32 v19, v18, v200
	v_mul_f32_e32 v12, v120, v22
	v_mul_f32_e32 v13, v121, v23
	v_mul_f32_e32 v14, v122, v24
	v_mul_f32_e32 v15, v123, v25
	v_cvt_pk_bf16_f32 v16, v12, v13
	v_cvt_pk_bf16_f32 v17, v14, v15
	v_mul_f32_e32 v22, v76, v1
	v_mul_f32_e32 v23, v77, v1
	v_mul_f32_e32 v24, v78, v1
	v_mul_f32_e32 v25, v79, v1
	ds_write_b64 v19, v[16:17]
	v_add_u32_e32 v19, v18, v201
	v_mul_f32_e32 v12, v22, v124
	v_mul_f32_e32 v13, v23, v125
	v_mul_f32_e32 v14, v24, v126
	v_mul_f32_e32 v15, v25, v127
	v_cvt_pk_bf16_f32 v16, v12, v13
	v_cvt_pk_bf16_f32 v17, v14, v15
	v_mul_f32_e32 v22, v48, v1
	v_mul_f32_e32 v23, v49, v1
	v_mul_f32_e32 v24, v50, v1
	v_mul_f32_e32 v25, v51, v1
	ds_write_b64 v19, v[16:17]
	v_add_u32_e32 v19, v18, v202
	v_mul_f32_e32 v12, v22, v128
	v_mul_f32_e32 v13, v23, v129
	v_mul_f32_e32 v14, v24, v130
	v_mul_f32_e32 v15, v25, v131
	v_cvt_pk_bf16_f32 v16, v12, v13
	v_cvt_pk_bf16_f32 v17, v14, v15
; __device__ __forceinline__ unsigned cvt_pk_bf16(float lo, float hi) { unsigned r; asm volatile("v_cvt_pk_bf16_f32 %0, %1, %2" : "=v"(r) : "v"(lo), "v"(hi)); return r; }
; #define ATT_LAS __attribute__((address_space(3)))
; __device__ __forceinline__ void diff_unit(ATT_LAS unsigned char* lds, int b, int h, int qb, const bf16_t* __restrict__ DQ, const bf16_t* __restrict__ DK, const bf16_t* __restrict__ VT,
;                                           float lam, const float* __restrict__ gout, bf16_t* __restrict__ MIXED) {
;     ...
;             for (int g4 = 0; g4 < 4; ++g4) { const int e0 = 32 * e + 8 * g4 + 4 * hh; const f32x4 g = *(const f32x4*)(gout + e0);
;                 u32x2 w; w.x = cvt_pk_bf16(O[e][4 * g4] * rstd * g[0], O[e][4 * g4 + 1] * rstd * g[1]); w.y = cvt_pk_bf16(O[e][4 * g4 + 2] * rstd * g[2], O[e][4 * g4 + 3] * rstd * g[3]);
;                 *(ATT_LAS u32x2*)(stg + r * OSTG_PITCH + e0 * 2) = w; }
;         asm volatile("s_waitcnt lgkmcnt(0)" ::: "memory");
;         bf16_t* obase = MIXED + (size_t)(b * 4096 + t0w) * 2048 + h * 128;
; #pragma unroll
;         for (int i = 0; i < 8; ++i) { const int c = lane + 64 * i, row = c >> 4, c16 = c & 15;
;             *(u32x4*)(obase + (size_t)row * 2048 + c16 * 8) = *(const ATT_LAS u32x4*)(stg + row * OSTG_PITCH + c16 * 16); }
	v_mul_f32_e32 v22, v52, v1
	v_mul_f32_e32 v23, v53, v1
	v_mul_f32_e32 v24, v54, v1
	v_mul_f32_e32 v25, v55, v1
	ds_write_b64 v19, v[16:17]
	v_add_u32_e32 v19, v18, v203
	v_mul_f32_e32 v12, v22, v132
	v_mul_f32_e32 v13, v23, v133
	v_mul_f32_e32 v14, v24, v134
	v_mul_f32_e32 v15, v25, v135
	v_cvt_pk_bf16_f32 v16, v12, v13
	v_cvt_pk_bf16_f32 v17, v14, v15
	v_mul_f32_e32 v22, v56, v1
	v_mul_f32_e32 v23, v57, v1
	v_mul_f32_e32 v24, v58, v1
	v_mul_f32_e32 v25, v59, v1
	ds_write_b64 v19, v[16:17]
	v_add_u32_e32 v19, v18, v204
	v_mul_f32_e32 v12, v22, v136
	v_mul_f32_e32 v13, v23, v137
	v_mul_f32_e32 v14, v24, v138
	v_mul_f32_e32 v15, v25, v139
	v_cvt_pk_bf16_f32 v16, v12, v13
	v_cvt_pk_bf16_f32 v17, v14, v15
	v_mul_f32_e32 v22, v60, v1
	v_mul_f32_e32 v23, v61, v1
	v_mul_f32_e32 v24, v62, v1
	v_mul_f32_e32 v25, v63, v1
	ds_write_b64 v19, v[16:17]
	v_add_u32_e32 v19, v18, v205
	v_mul_f32_e32 v12, v22, v140
	v_mul_f32_e32 v13, v23, v141
	v_mul_f32_e32 v14, v24, v142
	v_mul_f32_e32 v15, v25, v143
	v_cvt_pk_bf16_f32 v16, v12, v13
	v_cvt_pk_bf16_f32 v17, v14, v15
	v_mul_f32_e32 v22, v32, v1
	v_mul_f32_e32 v23, v33, v1
	v_mul_f32_e32 v24, v34, v1
	v_mul_f32_e32 v25, v35, v1
	ds_write_b64 v19, v[16:17]
	v_add_u32_e32 v19, v18, v206
	v_mul_f32_e32 v12, v22, v218
	v_mul_f32_e32 v13, v23, v219
	v_mul_f32_e32 v14, v24, v220
	v_mul_f32_e32 v15, v25, v221
	v_cvt_pk_bf16_f32 v16, v12, v13
	v_cvt_pk_bf16_f32 v17, v14, v15
	v_mul_f32_e32 v22, v36, v1
	v_mul_f32_e32 v23, v37, v1
	v_mul_f32_e32 v24, v38, v1
	v_mul_f32_e32 v25, v39, v1
	ds_write_b64 v19, v[16:17]
	v_add_u32_e32 v19, v18, v207
	v_mul_f32_e32 v12, v22, v222
	v_mul_f32_e32 v13, v23, v223
	v_mul_f32_e32 v14, v24, v224
	v_mul_f32_e32 v15, v25, v225
	v_cvt_pk_bf16_f32 v16, v12, v13
	v_cvt_pk_bf16_f32 v17, v14, v15
	v_mul_f32_e32 v22, v40, v1
	v_mul_f32_e32 v23, v41, v1
	v_mul_f32_e32 v24, v42, v1
	v_mul_f32_e32 v25, v43, v1
	ds_write_b64 v19, v[16:17]
	v_add_u32_e32 v19, v18, v208
	v_mul_f32_e32 v12, v22, v226
	v_mul_f32_e32 v13, v23, v227
	v_mul_f32_e32 v14, v24, v228
	v_mul_f32_e32 v15, v25, v229
	v_cvt_pk_bf16_f32 v16, v12, v13
	v_cvt_pk_bf16_f32 v17, v14, v15
	v_mul_f32_e32 v22, v44, v1
	v_mul_f32_e32 v23, v45, v1
	v_mul_f32_e32 v24, v46, v1
	v_mul_f32_e32 v25, v47, v1
	ds_write_b64 v19, v[16:17]
	v_add_u32_e32 v19, v18, v209
	v_mul_f32_e32 v12, v22, v230
	v_mul_f32_e32 v13, v23, v231
	v_mul_f32_e32 v14, v24, v232
	v_mul_f32_e32 v15, v25, v233
	v_cvt_pk_bf16_f32 v16, v12, v13
	v_cvt_pk_bf16_f32 v17, v14, v15
	v_mul_f32_e32 v22, v80, v1
	v_mul_f32_e32 v23, v81, v1
	v_mul_f32_e32 v24, v82, v1
	v_mul_f32_e32 v25, v83, v1
	ds_write_b64 v19, v[16:17]
	v_add_u32_e32 v19, v18, v210
	v_mul_f32_e32 v1, v3, v1
	v_mul_f32_e32 v12, v22, v234
	v_mul_f32_e32 v13, v23, v235
	v_mul_f32_e32 v14, v24, v236
	v_mul_f32_e32 v15, v25, v237
	v_cvt_pk_bf16_f32 v16, v12, v13
	v_cvt_pk_bf16_f32 v17, v14, v15
	ds_write_b64 v19, v[16:17]
	v_add_u32_e32 v16, v18, v211
	v_mul_f32_e32 v12, v20, v240
	v_mul_f32_e32 v13, v21, v241
	v_mul_f32_e32 v10, v10, v242
	v_mul_f32_e32 v11, v11, v243
	v_cvt_pk_bf16_f32 v14, v12, v13
	v_cvt_pk_bf16_f32 v15, v10, v11
	ds_write_b64 v16, v[14:15]
	v_add_u32_e32 v14, v18, v212
	v_add_u32_e32 v15, v18, v213
	v_mul_f32_e32 v8, v8, v244
	v_mul_f32_e32 v9, v9, v245
	v_mul_f32_e32 v6, v6, v246
	v_mul_f32_e32 v7, v7, v247
	v_cvt_pk_bf16_f32 v10, v8, v9
	v_cvt_pk_bf16_f32 v11, v6, v7
	ds_write_b64 v14, v[10:11]
	v_lshl_add_u64 v[12:13], s[22:23], 0, v[160:161]
	v_lshl_add_u64 v[34:35], v[12:13], 0, v[166:167]
	v_lshl_add_u64 v[36:37], v[12:13], 0, v[168:169]
	v_lshl_add_u64 v[38:39], v[12:13], 0, v[170:171]
	v_lshl_add_u64 v[40:41], v[12:13], 0, v[172:173]
	v_lshl_add_u64 v[42:43], v[12:13], 0, v[174:175]
	v_lshl_add_u64 v[44:45], v[12:13], 0, v[176:177]
	v_lshl_add_u64 v[46:47], v[12:13], 0, v[178:179]
	v_lshl_add_u64 v[48:49], v[12:13], 0, v[180:181]
	v_mul_f32_e32 v3, v4, v248
	v_mul_f32_e32 v4, v5, v249
	v_mul_f32_e32 v5, v2, v250
	v_mul_f32_e32 v1, v1, v251
	v_cvt_pk_bf16_f32 v2, v3, v4
	v_cvt_pk_bf16_f32 v3, v5, v1
	ds_write_b64 v15, v[2:3]
	s_waitcnt lgkmcnt(0)
	ds_read_b128 v[2:5], v30
	ds_read_b128 v[6:9], v30 offset:1088
	ds_read_b128 v[10:13], v30 offset:2176
	ds_read_b128 v[14:17], v30 offset:3264
	ds_read_b128 v[18:21], v30 offset:4352
	ds_read_b128 v[22:25], v30 offset:5440
	ds_read_b128 v[26:29], v30 offset:6528
	ds_read_b128 v[30:33], v30 offset:7616
	s_waitcnt lgkmcnt(7)
	global_store_dwordx4 v[34:35], v[2:5], off
	s_waitcnt lgkmcnt(6)
	global_store_dwordx4 v[36:37], v[6:9], off
	s_waitcnt lgkmcnt(5)
	global_store_dwordx4 v[38:39], v[10:13], off
	s_waitcnt lgkmcnt(4)
	global_store_dwordx4 v[40:41], v[14:17], off
	s_waitcnt lgkmcnt(3)
	global_store_dwordx4 v[42:43], v[18:21], off
	s_waitcnt lgkmcnt(2)
	global_store_dwordx4 v[44:45], v[22:25], off
	s_waitcnt lgkmcnt(1)
	global_store_dwordx4 v[46:47], v[26:29], off
	s_waitcnt lgkmcnt(0)
	global_store_dwordx4 v[48:49], v[30:33], off
	s_branch .LBB0_527
